# attention work items dealt to blocks in alternating order (balanced per-block work in NSA and FoX phases)
# speedup vs baseline: 1.0190x; 1.0039x over previous
.LBB0_456:
	s_ashr_i32 s15, s2, 6
	s_and_b32 s76, s15, 7
	s_sub_i32 s77, 7, s76
	s_bitcmp1_b32 s15, 3
	s_cselect_b32 s76, s77, s76
	s_andn2_b32 s15, s15, 7
	s_or_b32 s15, s15, s76
	s_sub_i32 s11, 63, s15
	s_lshl_b32 s6, s11, 7
	s_and_b32 s3, s2, 63
	v_add_u32_e32 v116, s6, v135
	s_lshl_b32 s12, s3, 13
	v_ashrrev_i32_e32 v117, 31, v116
	v_lshl_add_u64 v[2:3], s[12:13], 0, v[116:117]
	v_lshlrev_b64 v[2:3], 7, v[2:3]
	s_lshl_b32 s7, s3, 15
	v_lshl_add_u64 v[2:3], v[110:111], 0, v[2:3]
	s_add_u32 s16, s60, s7
	s_mov_b32 s7, s13
	global_load_dwordx4 v[66:69], v[2:3], off
	global_load_dwordx4 v[70:73], v[2:3], off offset:32
	global_load_dwordx4 v[74:77], v[2:3], off offset:64
	global_load_dwordx4 v[78:81], v[2:3], off offset:96
	s_addc_u32 s17, s61, 0
	s_lshl_b64 s[18:19], s[6:7], 2
	v_lshl_add_u64 v[2:3], v[116:117], 2, s[16:17]
	s_add_u32 s18, s16, s18
	s_addc_u32 s19, s17, s19
	global_load_dword v34, v[2:3], off
	s_nop 0
	global_load_dword v2, v103, s[18:19]
	s_lshl_b32 s20, s11, 1
	s_or_b32 s22, s20, 1
	s_lshl_b32 s7, s15, 7
	s_sub_i32 s12, 0x1fbf, s7
	s_mov_b32 s11, s22
	s_branch .LBB0_458

.LBB0_1923:
	s_lshr_b32 s99, s66, 3
	s_and_b32 s100, s99, 63
	s_sub_i32 s101, 63, s100
	s_bitcmp1_b32 s99, 6
	s_cselect_b32 s100, s101, s100
	s_andn2_b32 s99, s99, 63
	s_or_b32 s99, s99, s100
	s_lshl_b32 s99, s99, 3
	s_and_b32 s100, s66, 7
	s_or_b32 s99, s99, s100
	s_lshl_b32 s100, s99, 1
	s_and_b32 s68, s100, -16
	s_sub_i32 s30, 0x1ff0, s68
	s_sub_i32 s20, 0x1df1, s68
	s_lshr_b32 s74, s30, 6
	s_max_i32 s69, s20, 0
	s_max_u32 s73, s74, 64
	s_mov_b64 s[22:23], 0
	v_mov_b32_e32 v2, v175
	s_mov_b32 s24, s39
	s_barrier
	s_branch .LBB0_1925

.LBB0_1929:
	s_or_b64 exec, exec, s[22:23]
	s_lshl_b32 s20, s99, 1
	s_and_b32 s70, s20, -16
	s_sub_i32 s67, 0x1ff0, s70
	v_add_u32_e32 v132, s67, v103
	s_lshl_b32 s20, s99, 12
	s_and_b32 s54, s20, 0x6000
	s_mov_b32 s55, s39
	v_ashrrev_i32_e32 v133, 31, v132
	s_lshl_b32 s20, s99, 3
	v_lshl_add_u64 v[2:3], v[132:133], 0, s[54:55]
	s_and_b32 s55, s20, 8
	v_lshlrev_b64 v[4:5], 11, v[2:3]
	v_or_b32_e32 v6, s55, v102
	v_lshl_add_u64 v[4:5], s[42:43], 0, v[4:5]
	v_lshlrev_b32_e32 v104, 7, v6
	v_mad_u64_u32 v[6:7], s[20:21], v2, s49, v[124:125]
	v_lshl_add_u64 v[4:5], v[4:5], 0, v[104:105]
	v_mad_i32_i24 v7, v3, s49, v7
	s_lshl_b32 s20, s55, 2
	s_mov_b32 s21, s39
	v_lshl_add_u64 v[4:5], v[4:5], 0, v[122:123]
	v_lshl_add_u64 v[2:3], v[6:7], 0, s[20:21]
	global_load_dwordx4 v[66:69], v[4:5], off offset:32
	global_load_dwordx4 v[70:73], v[4:5], off offset:64
	global_load_dwordx4 v[74:77], v[4:5], off offset:96
	v_lshl_add_u64 v[130:131], v[2:3], 0, v[126:127]
	global_load_dwordx4 v[78:81], v[4:5], off
	global_load_dword v133, v[130:131], off
	global_load_dword v104, v[130:131], off offset:128
	s_and_b32 s20, s99, 7
	s_lshl_b32 s38, s20, 16
	s_lshr_b32 s20, s30, 4
	s_add_i32 s20, s20, 63
	s_lshr_b32 s20, s20, 6
	s_sub_i32 s28, 0, s20
	s_lshr_b32 s20, s67, 4
	s_and_b32 s71, s99, 7
	s_add_i32 s20, s20, 63
	s_lshr_b32 s29, s20, 6
	s_lshl_b32 s30, s71, 16
	s_add_u32 s22, s26, s30
	s_addc_u32 s23, s27, 0
	s_cmpk_lg_i32 s70, 0x1ff0
	s_cselect_b64 s[24:25], -1, 0
	s_cmpk_eq_i32 s70, 0x1ff0
	v_mov_b32_e32 v54, 0
	s_cbranch_scc1 .LBB0_1942
	v_mov_b32_e32 v129, v105
	v_lshl_add_u64 v[2:3], s[22:23], 0, v[128:129]
	v_lshl_add_u64 v[4:5], v[2:3], 0, v[106:107]
	v_lshl_add_u64 v[6:7], v[2:3], 0, v[108:109]
	global_load_dwordx4 v[34:37], v[4:5], off
	global_load_dwordx4 v[38:41], v[6:7], off
	s_cmp_eq_u32 s29, 1
	s_waitcnt vmcnt(1)
	ds_write_b128 v153, v[34:37]
	s_waitcnt vmcnt(0)
	ds_write_b128 v155, v[38:41]
	s_cbranch_scc1 .LBB0_1932
	v_lshl_add_u64 v[2:3], v[2:3], 0, s[40:41]
	v_lshl_add_u64 v[4:5], v[2:3], 0, v[106:107]
	v_lshl_add_u64 v[2:3], v[2:3], 0, v[108:109]
	global_load_dwordx4 v[34:37], v[4:5], off
	global_load_dwordx4 v[38:41], v[2:3], off
